# attention live steps: bias and row-max tree issued inside the P.V MFMA sequence (5 VALU per gap)
# baseline (speedup 1.0000x reference)
; template <int D0> __device__ __forceinline__ void pv_one(f32x16& od, int vb, bf16x8 pa0, bf16x8 pa1, bf16x8 pa2, bf16x8 pa3) {
;   const s16x4 l0 = tr_read<v_rd_off(D0, 0, 0)>(vb), h0 = tr_read<v_rd_off(D0, 0, 1)>(vb), l1 = tr_read<v_rd_off(D0, 1, 0)>(vb), h1 = tr_read<v_rd_off(D0, 1, 1)>(vb);
;   const s16x4 l2 = tr_read<v_rd_off(D0, 2, 0)>(vb), h2 = tr_read<v_rd_off(D0, 2, 1)>(vb), l3 = tr_read<v_rd_off(D0, 3, 0)>(vb), h3 = tr_read<v_rd_off(D0, 3, 1)>(vb);
;   asm volatile("s_waitcnt lgkmcnt(0)" ::: "memory"); SBAR();
;     ...
;   od = __builtin_amdgcn_mfma_f32_32x32x16_bf16(pa0, PK(l0, h0), od, 0, 0, 0);
;   od = __builtin_amdgcn_mfma_f32_32x32x16_bf16(pa1, PK(l1, h1), od, 0, 0, 0);
;   od = __builtin_amdgcn_mfma_f32_32x32x16_bf16(pa2, PK(l2, h2), od, 0, 0, 0);
;   od = __builtin_amdgcn_mfma_f32_32x32x16_bf16(pa3, PK(l3, h3), od, 0, 0, 0);
;     ...
; }
; __device__ __forceinline__ void pv_d0(f32x16* o, int vb, bf16x8 pa0, bf16x8 pa1, bf16x8 pa2, bf16x8 pa3) {
;   pv_one<0>(o[0], vb, pa0, pa1, pa2, pa3); pv_one<1>(o[1], vb, pa0, pa1, pa2, pa3); pv_one<2>(o[2], vb, pa0, pa1, pa2, pa3); pv_one<3>(o[3], vb, pa0, pa1, pa2, pa3);
; }
; __device__ __forceinline__ void qkt_c(f32x16& p0, f32x16& p1, const char* Ks, const bf16x8* qr, const f32x16& negm, int r32, int hi) {
; #pragma unroll
;   for (int d0 = 0; d0 < 4; ++d0) { const int cb = (d0 * 16 + hi * 8) * 2;
;     bf16x8 b0 = *reinterpret_cast<const bf16x8*>(Ks + KSWZ(r32, cb));
;     bf16x8 b1 = *reinterpret_cast<const bf16x8*>(Ks + KSWZ(32 + r32, cb));
;     if (d0 == 0) { p0 = __builtin_amdgcn_mfma_f32_32x32x16_bf16(b0, qr[0], negm, 0, 0, 0); p1 = __builtin_amdgcn_mfma_f32_32x32x16_bf16(b1, qr[0], negm, 0, 0, 0); }
;     else { p0 = __builtin_amdgcn_mfma_f32_32x32x16_bf16(b0, qr[d0], p0, 0, 0, 0); p1 = __builtin_amdgcn_mfma_f32_32x32x16_bf16(b1, qr[d0], p1, 0, 0, 0); } }
; }
; template <int R> __device__ __forceinline__ void bias_r(f32x16& p0, f32x16& p1, float dq, float nslope) {
;   constexpr int C0 = (R & 3) + 8 * (R >> 2);
;   float x0, x1, a0 = p0[R], a1 = p1[R];
;   asm("v_sub_f32_e32 %0, %1, %2" : "=v"(x0) : "n"(__builtin_bit_cast(int, (float)C0)), "v"(dq));
;   asm("v_sub_f32_e32 %0, %1, %2" : "=v"(x1) : "n"(__builtin_bit_cast(int, (float)(C0 + 32))), "v"(dq));
;   asm("v_fma_f32 %0, %1, |%2|, %0" : "+v"(a0) : "v"(nslope), "v"(x0));
;   asm("v_fma_f32 %0, %1, |%2|, %0" : "+v"(a1) : "v"(nslope), "v"(x1));
.LBB0_364:
	ds_read_b128 v[114:117], v195 offset:32768
	ds_read_b128 v[204:207], v195 offset:40960
	s_and_b64 vcc, exec, s[14:15]
	s_waitcnt lgkmcnt(1)
	v_mfma_f32_32x32x16_bf16 v[98:113], v[114:117], v[130:133], v[82:97]
	s_waitcnt lgkmcnt(0)
	v_mfma_f32_32x32x16_bf16 v[114:129], v[204:207], v[130:133], v[82:97]
	ds_read_b128 v[204:207], v196 offset:32768
	s_waitcnt lgkmcnt(0)
	v_mfma_f32_32x32x16_bf16 v[98:113], v[204:207], v[134:137], v[98:113]
	ds_read_b128 v[204:207], v196 offset:40960
	s_waitcnt lgkmcnt(0)
	v_mfma_f32_32x32x16_bf16 v[114:129], v[204:207], v[134:137], v[114:129]
	ds_read_b128 v[204:207], v197 offset:32768
	s_waitcnt lgkmcnt(0)
	v_mfma_f32_32x32x16_bf16 v[98:113], v[204:207], v[138:141], v[98:113]
	ds_read_b128 v[204:207], v197 offset:40960
	s_waitcnt lgkmcnt(0)
	v_mfma_f32_32x32x16_bf16 v[114:129], v[204:207], v[138:141], v[114:129]
	ds_read_b128 v[204:207], v198 offset:32768
	s_waitcnt lgkmcnt(0)
	v_mfma_f32_32x32x16_bf16 v[98:113], v[204:207], v[142:145], v[98:113]
	ds_read_b128 v[204:207], v198 offset:40960
	s_waitcnt lgkmcnt(0)
	v_mfma_f32_32x32x16_bf16 v[114:129], v[204:207], v[142:145], v[114:129]
	s_cbranch_vccnz .LBB0_366
	s_add_i32 s72, s22, s46
	s_cmp_lt_i32 s46, s23
	s_cselect_b32 s14, s72, s39
	s_lshl_b32 s14, s14, 6
	v_cvt_f32_i32_e32 v0, s14
	v_sub_f32_e32 v0, v192, v0
	ds_read_b64_tr_b16 v[204:205], v194 offset:0
	ds_read_b64_tr_b16 v[206:207], v194 offset:0x800
	ds_read_b64_tr_b16 v[208:209], v194 offset:0x1000
	ds_read_b64_tr_b16 v[210:211], v194 offset:0x1800
	ds_read_b64_tr_b16 v[212:213], v194 offset:0x2000
	ds_read_b64_tr_b16 v[214:215], v194 offset:0x2800
	ds_read_b64_tr_b16 v[216:217], v194 offset:0x3000
	ds_read_b64_tr_b16 v[218:219], v194 offset:0x3800
	s_waitcnt lgkmcnt(0)
	s_nop 0
	v_mfma_f32_32x32x16_bf16 v[64:79], v[2:5], v[204:207], v[64:79]
	v_sub_f32_e32 v14, 0, v0
	v_sub_f32_e32 v15, 0x42000000, v0
	v_fma_f32 v98, v81, |v14|, v98
	v_sub_f32_e32 v14, 0x3f800000, v0
	v_fma_f32 v114, v81, |v15|, v114
	ds_read_b64_tr_b16 v[204:205], v194 offset:0x200
	ds_read_b64_tr_b16 v[206:207], v194 offset:0xa00
	v_mfma_f32_32x32x16_bf16 v[64:79], v[6:9], v[208:211], v[64:79]
	v_sub_f32_e32 v15, 0x42040000, v0
	v_fma_f32 v99, v81, |v14|, v99
	v_sub_f32_e32 v14, 0x40000000, v0
	v_fma_f32 v115, v81, |v15|, v115
	v_sub_f32_e32 v15, 0x42080000, v0
	ds_read_b64_tr_b16 v[208:209], v194 offset:0x1200
	ds_read_b64_tr_b16 v[210:211], v194 offset:0x1a00
	v_mfma_f32_32x32x16_bf16 v[64:79], v[10:13], v[212:215], v[64:79]
	v_fma_f32 v100, v81, |v14|, v100
	v_sub_f32_e32 v14, 0x40400000, v0
	v_fma_f32 v116, v81, |v15|, v116
	v_sub_f32_e32 v15, 0x420c0000, v0
	v_fma_f32 v101, v81, |v14|, v101
	ds_read_b64_tr_b16 v[212:213], v194 offset:0x2200
	ds_read_b64_tr_b16 v[214:215], v194 offset:0x2a00
	ds_read_b64_tr_b16 v[220:221], v194 offset:0x3200
	ds_read_b64_tr_b16 v[222:223], v194 offset:0x3a00
	s_waitcnt lgkmcnt(0)
	v_mfma_f32_32x32x16_bf16 v[64:79], v[162:165], v[216:219], v[64:79]
	v_sub_f32_e32 v14, 0x41000000, v0
	v_fma_f32 v117, v81, |v15|, v117
	v_sub_f32_e32 v15, 0x42200000, v0
	v_fma_f32 v102, v81, |v14|, v102
	v_sub_f32_e32 v14, 0x41100000, v0
	v_mfma_f32_32x32x16_bf16 v[48:63], v[2:5], v[204:207], v[48:63]
	v_fma_f32 v118, v81, |v15|, v118
	v_sub_f32_e32 v15, 0x42240000, v0
	v_fma_f32 v103, v81, |v14|, v103
	v_sub_f32_e32 v14, 0x41200000, v0
	v_fma_f32 v119, v81, |v15|, v119
	ds_read_b64_tr_b16 v[204:205], v194 offset:0x400
	ds_read_b64_tr_b16 v[206:207], v194 offset:0xc00
	v_mfma_f32_32x32x16_bf16 v[48:63], v[6:9], v[208:211], v[48:63]
	v_sub_f32_e32 v15, 0x42280000, v0
	v_fma_f32 v104, v81, |v14|, v104
	v_sub_f32_e32 v14, 0x41300000, v0
	v_fma_f32 v120, v81, |v15|, v120
	v_sub_f32_e32 v15, 0x422c0000, v0
	ds_read_b64_tr_b16 v[208:209], v194 offset:0x1400
	ds_read_b64_tr_b16 v[210:211], v194 offset:0x1c00
	v_mfma_f32_32x32x16_bf16 v[48:63], v[10:13], v[212:215], v[48:63]
	v_fma_f32 v105, v81, |v14|, v105
	v_sub_f32_e32 v14, 0x41800000, v0
	v_fma_f32 v121, v81, |v15|, v121
	v_sub_f32_e32 v15, 0x42400000, v0
	v_fma_f32 v106, v81, |v14|, v106
	ds_read_b64_tr_b16 v[212:213], v194 offset:0x2400
	ds_read_b64_tr_b16 v[214:215], v194 offset:0x2c00
	ds_read_b64_tr_b16 v[216:217], v194 offset:0x3400
	ds_read_b64_tr_b16 v[218:219], v194 offset:0x3c00
	s_waitcnt lgkmcnt(0)
	v_mfma_f32_32x32x16_bf16 v[48:63], v[162:165], v[220:223], v[48:63]
	v_sub_f32_e32 v14, 0x41880000, v0
	v_fma_f32 v122, v81, |v15|, v122
	v_sub_f32_e32 v15, 0x42440000, v0
	v_fma_f32 v107, v81, |v14|, v107
	v_sub_f32_e32 v14, 0x41900000, v0
	v_mfma_f32_32x32x16_bf16 v[32:47], v[2:5], v[204:207], v[32:47]
	v_fma_f32 v123, v81, |v15|, v123
	v_sub_f32_e32 v15, 0x42480000, v0
	v_fma_f32 v108, v81, |v14|, v108
	v_sub_f32_e32 v14, 0x41980000, v0
	v_fma_f32 v124, v81, |v15|, v124
	ds_read_b64_tr_b16 v[204:205], v194 offset:0x600
	ds_read_b64_tr_b16 v[206:207], v194 offset:0xe00
	v_mfma_f32_32x32x16_bf16 v[32:47], v[6:9], v[208:211], v[32:47]
	v_sub_f32_e32 v15, 0x424c0000, v0
	v_fma_f32 v109, v81, |v14|, v109
	v_sub_f32_e32 v14, 0x41c00000, v0
	v_fma_f32 v125, v81, |v15|, v125
	v_sub_f32_e32 v15, 0x42600000, v0
	ds_read_b64_tr_b16 v[208:209], v194 offset:0x1600
	ds_read_b64_tr_b16 v[210:211], v194 offset:0x1e00
	v_mfma_f32_32x32x16_bf16 v[32:47], v[10:13], v[212:215], v[32:47]
	v_fma_f32 v110, v81, |v14|, v110
	v_sub_f32_e32 v14, 0x41c80000, v0
	v_fma_f32 v126, v81, |v15|, v126
	v_sub_f32_e32 v15, 0x42640000, v0
	v_fma_f32 v111, v81, |v14|, v111
	ds_read_b64_tr_b16 v[212:213], v194 offset:0x2600
	ds_read_b64_tr_b16 v[214:215], v194 offset:0x2e00
	ds_read_b64_tr_b16 v[220:221], v194 offset:0x3600
	ds_read_b64_tr_b16 v[222:223], v194 offset:0x3e00
	s_waitcnt lgkmcnt(0)
	v_mfma_f32_32x32x16_bf16 v[32:47], v[162:165], v[216:219], v[32:47]
	v_sub_f32_e32 v14, 0x41d00000, v0
	v_fma_f32 v127, v81, |v15|, v127
	v_sub_f32_e32 v15, 0x42680000, v0
	v_fma_f32 v112, v81, |v14|, v112
	v_sub_f32_e32 v14, 0x41d80000, v0
	v_mfma_f32_32x32x16_bf16 v[16:31], v[2:5], v[204:207], v[16:31]
	v_sub_f32_e32 v0, 0x426c0000, v0
	v_fma_f32 v128, v81, |v15|, v128
	v_fma_f32 v113, v81, |v14|, v113
	v_fma_f32 v129, v81, |v0|, v129
	v_max_f32_e32 v0, v99, v99
	v_mfma_f32_32x32x16_bf16 v[16:31], v[6:9], v[208:211], v[16:31]
	v_max_f32_e32 v14, v98, v98
	v_max_f32_e32 v0, v14, v0
	v_max3_f32 v14, v100, v101, v115
	v_max3_f32 v0, v0, v114, v116
	v_max3_f32 v0, v0, v117, v102
	v_max3_f32 v14, v14, v104, v105
	v_max3_f32 v0, v0, v103, v118
	v_max3_f32 v14, v14, v120, v121
	v_mfma_f32_32x32x16_bf16 v[16:31], v[10:13], v[212:215], v[16:31]
	v_max3_f32 v0, v0, v119, v106
	v_max3_f32 v14, v14, v108, v109
	v_max3_f32 v0, v0, v107, v122
	v_max3_f32 v14, v14, v124, v125
	v_max3_f32 v0, v0, v123, v110
	v_max3_f32 v14, v14, v112, v113
	v_max3_f32 v0, v0, v111, v126
	v_max3_f32 v14, v14, v128, v129
	v_mfma_f32_32x32x16_bf16 v[16:31], v[162:165], v[220:223], v[16:31]
	v_max3_f32 v0, v0, v127, v14
	v_mov_b32_e32 v14, v0
	s_nop 1
	v_permlane32_swap_b32_e32 v0, v14
	v_max_f32_e32 v14, v14, v14
	v_max_f32_e32 v0, v0, v0
	v_max_f32_e32 v167, v0, v14
	s_barrier
	s_branch .Lafter_max_0
; template <int R> __device__ __forceinline__ void bias_r(f32x16& p0, f32x16& p1, float dq, float nslope) {
;   constexpr int C0 = (R & 3) + 8 * (R >> 2);
;   float x0, x1, a0 = p0[R], a1 = p1[R];
;   asm("v_sub_f32_e32 %0, %1, %2" : "=v"(x0) : "n"(__builtin_bit_cast(int, (float)C0)), "v"(dq));
;   asm("v_sub_f32_e32 %0, %1, %2" : "=v"(x1) : "n"(__builtin_bit_cast(int, (float)(C0 + 32))), "v"(dq));
;   asm("v_fma_f32 %0, %1, |%2|, %0" : "+v"(a0) : "v"(nslope), "v"(x0));
;   asm("v_fma_f32 %0, %1, |%2|, %0" : "+v"(a1) : "v"(nslope), "v"(x1));
;   p0[R] = a0; p1[R] = a1;
;   if constexpr (R < 15) bias_r<R + 1>(p0, p1, dq, nslope);
; }
; __device__ __forceinline__ bool softmax_pp(f32x16& p0, f32x16& p1, float& m_reg, float& l_reg, f32x16& negm, float& alpha, float& m_run, float dq, float nslope,
;                                            bf16x8& pa0, bf16x8& pa1, bf16x8& pa2, bf16x8& pa3) {
;   bias_r<0>(p0, p1, dq, nslope);
;   float a = fmaxf(fmaxf(p0[0], p0[1]), p1[0]), bq = fmaxf(fmaxf(p0[2], p0[3]), p1[1]); a = fmaxf(fmaxf(a, p1[2]), p1[3]);
; #pragma unroll
;   for (int r = 4; r < 16; r += 4) { a = fmaxf(fmaxf(a, p0[r]), p0[r + 1]); bq = fmaxf(fmaxf(bq, p0[r + 2]), p0[r + 3]); a = fmaxf(fmaxf(a, p1[r]), p1[r + 1]); bq = fmaxf(fmaxf(bq, p1[r + 2]), p1[r + 3]); }
;   float pmax = fmaxf(a, bq);
;   { auto rr = __builtin_amdgcn_permlane32_swap(__float_as_uint(pmax), __float_as_uint(pmax), false, false);
;     pmax = fmaxf(__uint_as_float(rr[0]), __uint_as_float(rr[1])); }
.LBB0_366:
	s_add_i32 s72, s22, s46
	s_cmp_lt_i32 s46, s23
	s_cselect_b32 s14, s72, s39
	s_lshl_b32 s14, s14, 6
	v_cvt_f32_i32_e32 v0, s14
	s_barrier
	v_sub_f32_e32 v0, v192, v0
	v_sub_f32_e32 v14, 0, v0
	v_sub_f32_e32 v15, 0x42000000, v0
	s_nop 0
	v_fma_f32 v98, v81, |v14|, v98
	v_sub_f32_e32 v14, 0x3f800000, v0
	v_fma_f32 v114, v81, |v15|, v114
	v_sub_f32_e32 v15, 0x42040000, v0
	s_nop 0
	v_fma_f32 v99, v81, |v14|, v99
	v_sub_f32_e32 v14, 0x40000000, v0
	v_fma_f32 v115, v81, |v15|, v115
	v_sub_f32_e32 v15, 0x42080000, v0
	s_nop 0
	v_fma_f32 v100, v81, |v14|, v100
	v_sub_f32_e32 v14, 0x40400000, v0
	v_fma_f32 v116, v81, |v15|, v116
	v_sub_f32_e32 v15, 0x420c0000, v0
	s_nop 0
	v_fma_f32 v101, v81, |v14|, v101
	v_sub_f32_e32 v14, 0x41000000, v0
	v_fma_f32 v117, v81, |v15|, v117
	v_sub_f32_e32 v15, 0x42200000, v0
	s_nop 0
	v_fma_f32 v102, v81, |v14|, v102
	v_sub_f32_e32 v14, 0x41100000, v0
	v_fma_f32 v118, v81, |v15|, v118
	v_sub_f32_e32 v15, 0x42240000, v0
	s_nop 0
	v_fma_f32 v103, v81, |v14|, v103
	v_sub_f32_e32 v14, 0x41200000, v0
	v_fma_f32 v119, v81, |v15|, v119
	v_sub_f32_e32 v15, 0x42280000, v0
	s_nop 0
	v_fma_f32 v104, v81, |v14|, v104
	v_sub_f32_e32 v14, 0x41300000, v0
	v_fma_f32 v120, v81, |v15|, v120
	v_sub_f32_e32 v15, 0x422c0000, v0
	s_nop 0
	v_fma_f32 v105, v81, |v14|, v105
	v_sub_f32_e32 v14, 0x41800000, v0
	v_fma_f32 v121, v81, |v15|, v121
	v_sub_f32_e32 v15, 0x42400000, v0
	s_nop 0
	v_fma_f32 v106, v81, |v14|, v106
	v_sub_f32_e32 v14, 0x41880000, v0
	v_fma_f32 v122, v81, |v15|, v122
	v_sub_f32_e32 v15, 0x42440000, v0
	s_nop 0
	v_fma_f32 v107, v81, |v14|, v107
	v_sub_f32_e32 v14, 0x41900000, v0
	v_fma_f32 v123, v81, |v15|, v123
	v_sub_f32_e32 v15, 0x42480000, v0
	s_nop 0
	v_fma_f32 v108, v81, |v14|, v108
	v_sub_f32_e32 v14, 0x41980000, v0
	v_fma_f32 v124, v81, |v15|, v124
	v_sub_f32_e32 v15, 0x424c0000, v0
	s_nop 0
	v_fma_f32 v109, v81, |v14|, v109
	v_sub_f32_e32 v14, 0x41c00000, v0
	v_fma_f32 v125, v81, |v15|, v125
	v_sub_f32_e32 v15, 0x42600000, v0
	s_nop 0
	v_fma_f32 v110, v81, |v14|, v110
	v_sub_f32_e32 v14, 0x41c80000, v0
	v_fma_f32 v126, v81, |v15|, v126
	v_sub_f32_e32 v15, 0x42640000, v0
	s_nop 0
	v_fma_f32 v111, v81, |v14|, v111
	v_sub_f32_e32 v14, 0x41d00000, v0
	v_fma_f32 v127, v81, |v15|, v127
	v_sub_f32_e32 v15, 0x42680000, v0
	s_nop 0
	v_fma_f32 v112, v81, |v14|, v112
	v_sub_f32_e32 v14, 0x41d80000, v0
	v_sub_f32_e32 v0, 0x426c0000, v0
	v_fma_f32 v128, v81, |v15|, v128
	s_nop 0
	v_fma_f32 v113, v81, |v14|, v113
	v_fma_f32 v129, v81, |v0|, v129
	v_max_f32_e32 v0, v99, v99
	v_max_f32_e32 v14, v98, v98
	v_max_f32_e32 v0, v14, v0
	v_max3_f32 v14, v100, v101, v115
	v_max3_f32 v0, v0, v114, v116
	v_max3_f32 v0, v0, v117, v102
	v_max3_f32 v14, v14, v104, v105
	v_max3_f32 v0, v0, v103, v118
	v_max3_f32 v14, v14, v120, v121
	v_max3_f32 v0, v0, v119, v106
	v_max3_f32 v14, v14, v108, v109
	v_max3_f32 v0, v0, v107, v122
	v_max3_f32 v14, v14, v124, v125
	v_max3_f32 v0, v0, v123, v110
	v_max3_f32 v14, v14, v112, v113
	v_max3_f32 v0, v0, v111, v126
	v_max3_f32 v14, v14, v128, v129
	v_max3_f32 v0, v0, v127, v14
	v_mov_b32_e32 v14, v0
	s_nop 1
	v_permlane32_swap_b32_e32 v0, v14
	v_max_f32_e32 v14, v14, v14
	v_max_f32_e32 v0, v0, v0
	v_max_f32_e32 v167, v0, v14
.Lafter_max_0:
	v_pk_add_f32 v[14:15], v[172:173], v[166:167]
	s_nop 0
	v_cmp_lt_f32_e32 vcc, v15, v14
	s_cmp_lg_u64 vcc, exec
	s_cselect_b64 s[14:15], -1, 0
	s_cmp_eq_u64 vcc, exec
	s_cbranch_scc1 .LBB0_370
	v_cmp_ge_f32_e32 vcc, s59, v167
	s_cmp_eq_u64 vcc, exec
	s_cbranch_scc0 .LBB0_395
	v_mov_b32_e32 v0, 1.0

; template <int D0> __device__ __forceinline__ void pv_one(f32x16& od, int vb, bf16x8 pa0, bf16x8 pa1, bf16x8 pa2, bf16x8 pa3) {
;   const s16x4 l0 = tr_read<v_rd_off(D0, 0, 0)>(vb), h0 = tr_read<v_rd_off(D0, 0, 1)>(vb), l1 = tr_read<v_rd_off(D0, 1, 0)>(vb), h1 = tr_read<v_rd_off(D0, 1, 1)>(vb);
;   const s16x4 l2 = tr_read<v_rd_off(D0, 2, 0)>(vb), h2 = tr_read<v_rd_off(D0, 2, 1)>(vb), l3 = tr_read<v_rd_off(D0, 3, 0)>(vb), h3 = tr_read<v_rd_off(D0, 3, 1)>(vb);
;   asm volatile("s_waitcnt lgkmcnt(0)" ::: "memory"); SBAR();
;     ...
;   od = __builtin_amdgcn_mfma_f32_32x32x16_bf16(pa0, PK(l0, h0), od, 0, 0, 0);
;   od = __builtin_amdgcn_mfma_f32_32x32x16_bf16(pa1, PK(l1, h1), od, 0, 0, 0);
;   od = __builtin_amdgcn_mfma_f32_32x32x16_bf16(pa2, PK(l2, h2), od, 0, 0, 0);
;   od = __builtin_amdgcn_mfma_f32_32x32x16_bf16(pa3, PK(l3, h3), od, 0, 0, 0);
;     ...
; }
; __device__ __forceinline__ void pv_d0(f32x16* o, int vb, bf16x8 pa0, bf16x8 pa1, bf16x8 pa2, bf16x8 pa3) {
;   pv_one<0>(o[0], vb, pa0, pa1, pa2, pa3); pv_one<1>(o[1], vb, pa0, pa1, pa2, pa3); pv_one<2>(o[2], vb, pa0, pa1, pa2, pa3); pv_one<3>(o[3], vb, pa0, pa1, pa2, pa3);
; }
; __device__ __forceinline__ void qkt_c(f32x16& p0, f32x16& p1, const char* Ks, const bf16x8* qr, const f32x16& negm, int r32, int hi) {
; #pragma unroll
;   for (int d0 = 0; d0 < 4; ++d0) { const int cb = (d0 * 16 + hi * 8) * 2;
;     bf16x8 b0 = *reinterpret_cast<const bf16x8*>(Ks + KSWZ(r32, cb));
;     bf16x8 b1 = *reinterpret_cast<const bf16x8*>(Ks + KSWZ(32 + r32, cb));
;     if (d0 == 0) { p0 = __builtin_amdgcn_mfma_f32_32x32x16_bf16(b0, qr[0], negm, 0, 0, 0); p1 = __builtin_amdgcn_mfma_f32_32x32x16_bf16(b1, qr[0], negm, 0, 0, 0); }
;     else { p0 = __builtin_amdgcn_mfma_f32_32x32x16_bf16(b0, qr[d0], p0, 0, 0, 0); p1 = __builtin_amdgcn_mfma_f32_32x32x16_bf16(b1, qr[d0], p1, 0, 0, 0); } }
; }
; template <int R> __device__ __forceinline__ void bias_r(f32x16& p0, f32x16& p1, float dq, float nslope) {
;   constexpr int C0 = (R & 3) + 8 * (R >> 2);
;   float x0, x1, a0 = p0[R], a1 = p1[R];
;   asm("v_sub_f32_e32 %0, %1, %2" : "=v"(x0) : "n"(__builtin_bit_cast(int, (float)C0)), "v"(dq));
;   asm("v_sub_f32_e32 %0, %1, %2" : "=v"(x1) : "n"(__builtin_bit_cast(int, (float)(C0 + 32))), "v"(dq));
;   asm("v_fma_f32 %0, %1, |%2|, %0" : "+v"(a0) : "v"(nslope), "v"(x0));
;   asm("v_fma_f32 %0, %1, |%2|, %0" : "+v"(a1) : "v"(nslope), "v"(x1));
.LBB0_379:
	s_waitcnt lgkmcnt(0)
	s_barrier
	ds_read_b128 v[114:117], v195 offset:49152
	ds_read_b128 v[204:207], v195 offset:57344
	s_andn2_b64 vcc, exec, s[14:15]
	s_waitcnt lgkmcnt(1)
	v_mfma_f32_32x32x16_bf16 v[98:113], v[114:117], v[130:133], v[82:97]
	s_waitcnt lgkmcnt(0)
	v_mfma_f32_32x32x16_bf16 v[114:129], v[204:207], v[130:133], v[82:97]
	ds_read_b128 v[204:207], v196 offset:49152
	s_waitcnt lgkmcnt(0)
	v_mfma_f32_32x32x16_bf16 v[98:113], v[204:207], v[134:137], v[98:113]
	ds_read_b128 v[204:207], v196 offset:57344
	s_waitcnt lgkmcnt(0)
	v_mfma_f32_32x32x16_bf16 v[114:129], v[204:207], v[134:137], v[114:129]
	ds_read_b128 v[204:207], v197 offset:49152
	s_waitcnt lgkmcnt(0)
	v_mfma_f32_32x32x16_bf16 v[98:113], v[204:207], v[138:141], v[98:113]
	ds_read_b128 v[204:207], v197 offset:57344
	s_waitcnt lgkmcnt(0)
	v_mfma_f32_32x32x16_bf16 v[114:129], v[204:207], v[138:141], v[114:129]
	ds_read_b128 v[204:207], v198 offset:49152
	s_waitcnt lgkmcnt(0)
	v_mfma_f32_32x32x16_bf16 v[98:113], v[204:207], v[142:145], v[98:113]
	ds_read_b128 v[204:207], v198 offset:57344
	s_waitcnt lgkmcnt(0)
	v_mfma_f32_32x32x16_bf16 v[114:129], v[204:207], v[142:145], v[114:129]
	s_cbranch_vccnz .LBB0_381
	s_add_i32 s46, s47, -1
	s_add_i32 s72, s72, 1
	s_add_i32 s14, s39, -1
	s_cmp_lt_i32 s46, s23
	s_cselect_b32 s14, s72, s14
	s_lshl_b32 s14, s14, 6
	v_cvt_f32_i32_e32 v0, s14
	v_sub_f32_e32 v0, v192, v0
	ds_read_b64_tr_b16 v[204:205], v193 offset:0
	ds_read_b64_tr_b16 v[206:207], v193 offset:0x800
	ds_read_b64_tr_b16 v[208:209], v193 offset:0x1000
	ds_read_b64_tr_b16 v[210:211], v193 offset:0x1800
	ds_read_b64_tr_b16 v[212:213], v193 offset:0x2000
	ds_read_b64_tr_b16 v[214:215], v193 offset:0x2800
	ds_read_b64_tr_b16 v[216:217], v193 offset:0x3000
	ds_read_b64_tr_b16 v[218:219], v193 offset:0x3800
	s_waitcnt lgkmcnt(0)
	s_nop 0
	v_mfma_f32_32x32x16_bf16 v[64:79], v[2:5], v[204:207], v[64:79]
	v_sub_f32_e32 v14, 0, v0
	v_sub_f32_e32 v15, 0x42000000, v0
	v_fma_f32 v98, v81, |v14|, v98
	v_sub_f32_e32 v14, 0x3f800000, v0
	v_fma_f32 v114, v81, |v15|, v114
	ds_read_b64_tr_b16 v[204:205], v193 offset:0x200
	ds_read_b64_tr_b16 v[206:207], v193 offset:0xa00
	v_mfma_f32_32x32x16_bf16 v[64:79], v[6:9], v[208:211], v[64:79]
	v_sub_f32_e32 v15, 0x42040000, v0
	v_fma_f32 v99, v81, |v14|, v99
	v_sub_f32_e32 v14, 0x40000000, v0
	v_fma_f32 v115, v81, |v15|, v115
	v_sub_f32_e32 v15, 0x42080000, v0
	ds_read_b64_tr_b16 v[208:209], v193 offset:0x1200
	ds_read_b64_tr_b16 v[210:211], v193 offset:0x1a00
	v_mfma_f32_32x32x16_bf16 v[64:79], v[10:13], v[212:215], v[64:79]
	v_fma_f32 v100, v81, |v14|, v100
	v_sub_f32_e32 v14, 0x40400000, v0
	v_fma_f32 v116, v81, |v15|, v116
	v_sub_f32_e32 v15, 0x420c0000, v0
	v_fma_f32 v101, v81, |v14|, v101
	ds_read_b64_tr_b16 v[212:213], v193 offset:0x2200
	ds_read_b64_tr_b16 v[214:215], v193 offset:0x2a00
	ds_read_b64_tr_b16 v[220:221], v193 offset:0x3200
	ds_read_b64_tr_b16 v[222:223], v193 offset:0x3a00
	s_waitcnt lgkmcnt(0)
	v_mfma_f32_32x32x16_bf16 v[64:79], v[162:165], v[216:219], v[64:79]
	v_sub_f32_e32 v14, 0x41000000, v0
	v_fma_f32 v117, v81, |v15|, v117
	v_sub_f32_e32 v15, 0x42200000, v0
	v_fma_f32 v102, v81, |v14|, v102
	v_sub_f32_e32 v14, 0x41100000, v0
	v_mfma_f32_32x32x16_bf16 v[48:63], v[2:5], v[204:207], v[48:63]
	v_fma_f32 v118, v81, |v15|, v118
	v_sub_f32_e32 v15, 0x42240000, v0
	v_fma_f32 v103, v81, |v14|, v103
	v_sub_f32_e32 v14, 0x41200000, v0
	v_fma_f32 v119, v81, |v15|, v119
	ds_read_b64_tr_b16 v[204:205], v193 offset:0x400
	ds_read_b64_tr_b16 v[206:207], v193 offset:0xc00
	v_mfma_f32_32x32x16_bf16 v[48:63], v[6:9], v[208:211], v[48:63]
	v_sub_f32_e32 v15, 0x42280000, v0
	v_fma_f32 v104, v81, |v14|, v104
	v_sub_f32_e32 v14, 0x41300000, v0
	v_fma_f32 v120, v81, |v15|, v120
	v_sub_f32_e32 v15, 0x422c0000, v0
	ds_read_b64_tr_b16 v[208:209], v193 offset:0x1400
	ds_read_b64_tr_b16 v[210:211], v193 offset:0x1c00
	v_mfma_f32_32x32x16_bf16 v[48:63], v[10:13], v[212:215], v[48:63]
	v_fma_f32 v105, v81, |v14|, v105
	v_sub_f32_e32 v14, 0x41800000, v0
	v_fma_f32 v121, v81, |v15|, v121
	v_sub_f32_e32 v15, 0x42400000, v0
	v_fma_f32 v106, v81, |v14|, v106
	ds_read_b64_tr_b16 v[212:213], v193 offset:0x2400
	ds_read_b64_tr_b16 v[214:215], v193 offset:0x2c00
	ds_read_b64_tr_b16 v[216:217], v193 offset:0x3400
	ds_read_b64_tr_b16 v[218:219], v193 offset:0x3c00
	s_waitcnt lgkmcnt(0)
	v_mfma_f32_32x32x16_bf16 v[48:63], v[162:165], v[220:223], v[48:63]
	v_sub_f32_e32 v14, 0x41880000, v0
	v_fma_f32 v122, v81, |v15|, v122
	v_sub_f32_e32 v15, 0x42440000, v0
	v_fma_f32 v107, v81, |v14|, v107
	v_sub_f32_e32 v14, 0x41900000, v0
	v_mfma_f32_32x32x16_bf16 v[32:47], v[2:5], v[204:207], v[32:47]
	v_fma_f32 v123, v81, |v15|, v123
	v_sub_f32_e32 v15, 0x42480000, v0
	v_fma_f32 v108, v81, |v14|, v108
	v_sub_f32_e32 v14, 0x41980000, v0
	v_fma_f32 v124, v81, |v15|, v124
	ds_read_b64_tr_b16 v[204:205], v193 offset:0x600
	ds_read_b64_tr_b16 v[206:207], v193 offset:0xe00
	v_mfma_f32_32x32x16_bf16 v[32:47], v[6:9], v[208:211], v[32:47]
	v_sub_f32_e32 v15, 0x424c0000, v0
	v_fma_f32 v109, v81, |v14|, v109
	v_sub_f32_e32 v14, 0x41c00000, v0
	v_fma_f32 v125, v81, |v15|, v125
	v_sub_f32_e32 v15, 0x42600000, v0
	ds_read_b64_tr_b16 v[208:209], v193 offset:0x1600
	ds_read_b64_tr_b16 v[210:211], v193 offset:0x1e00
	v_mfma_f32_32x32x16_bf16 v[32:47], v[10:13], v[212:215], v[32:47]
	v_fma_f32 v110, v81, |v14|, v110
	v_sub_f32_e32 v14, 0x41c80000, v0
	v_fma_f32 v126, v81, |v15|, v126
	v_sub_f32_e32 v15, 0x42640000, v0
	v_fma_f32 v111, v81, |v14|, v111
	ds_read_b64_tr_b16 v[212:213], v193 offset:0x2600
	ds_read_b64_tr_b16 v[214:215], v193 offset:0x2e00
	ds_read_b64_tr_b16 v[220:221], v193 offset:0x3600
	ds_read_b64_tr_b16 v[222:223], v193 offset:0x3e00
	s_waitcnt lgkmcnt(0)
; template <int R> __device__ __forceinline__ void bias_r(f32x16& p0, f32x16& p1, float dq, float nslope) {
;   constexpr int C0 = (R & 3) + 8 * (R >> 2);
;   float x0, x1, a0 = p0[R], a1 = p1[R];
;   asm("v_sub_f32_e32 %0, %1, %2" : "=v"(x0) : "n"(__builtin_bit_cast(int, (float)C0)), "v"(dq));
;   asm("v_sub_f32_e32 %0, %1, %2" : "=v"(x1) : "n"(__builtin_bit_cast(int, (float)(C0 + 32))), "v"(dq));
;   asm("v_fma_f32 %0, %1, |%2|, %0" : "+v"(a0) : "v"(nslope), "v"(x0));
;   asm("v_fma_f32 %0, %1, |%2|, %0" : "+v"(a1) : "v"(nslope), "v"(x1));
;   p0[R] = a0; p1[R] = a1;
;   if constexpr (R < 15) bias_r<R + 1>(p0, p1, dq, nslope);
; }
; __device__ __forceinline__ bool softmax_pp(f32x16& p0, f32x16& p1, float& m_reg, float& l_reg, f32x16& negm, float& alpha, float& m_run, float dq, float nslope,
;                                            bf16x8& pa0, bf16x8& pa1, bf16x8& pa2, bf16x8& pa3) {
;   bias_r<0>(p0, p1, dq, nslope);
;   float a = fmaxf(fmaxf(p0[0], p0[1]), p1[0]), bq = fmaxf(fmaxf(p0[2], p0[3]), p1[1]); a = fmaxf(fmaxf(a, p1[2]), p1[3]);
; #pragma unroll
;   for (int r = 4; r < 16; r += 4) { a = fmaxf(fmaxf(a, p0[r]), p0[r + 1]); bq = fmaxf(fmaxf(bq, p0[r + 2]), p0[r + 3]); a = fmaxf(fmaxf(a, p1[r]), p1[r + 1]); bq = fmaxf(fmaxf(bq, p1[r + 2]), p1[r + 3]); }
;   float pmax = fmaxf(a, bq);
;   { auto rr = __builtin_amdgcn_permlane32_swap(__float_as_uint(pmax), __float_as_uint(pmax), false, false);
;     pmax = fmaxf(__uint_as_float(rr[0]), __uint_as_float(rr[1])); }
	v_mfma_f32_32x32x16_bf16 v[32:47], v[162:165], v[216:219], v[32:47]
	v_sub_f32_e32 v14, 0x41d00000, v0
	v_fma_f32 v127, v81, |v15|, v127
	v_sub_f32_e32 v15, 0x42680000, v0
	v_fma_f32 v112, v81, |v14|, v112
	v_sub_f32_e32 v14, 0x41d80000, v0
	v_mfma_f32_32x32x16_bf16 v[16:31], v[2:5], v[204:207], v[16:31]
	v_sub_f32_e32 v0, 0x426c0000, v0
	v_fma_f32 v128, v81, |v15|, v128
	v_fma_f32 v113, v81, |v14|, v113
	v_fma_f32 v129, v81, |v0|, v129
	v_max_f32_e32 v0, v99, v99
	v_mfma_f32_32x32x16_bf16 v[16:31], v[6:9], v[208:211], v[16:31]
	v_max_f32_e32 v14, v98, v98
	v_max_f32_e32 v0, v14, v0
	v_max3_f32 v14, v100, v101, v115
	v_max3_f32 v0, v0, v114, v116
	v_max3_f32 v0, v0, v117, v102
	v_max3_f32 v14, v14, v104, v105
	v_max3_f32 v0, v0, v103, v118
	v_max3_f32 v14, v14, v120, v121
	v_mfma_f32_32x32x16_bf16 v[16:31], v[10:13], v[212:215], v[16:31]
	v_max3_f32 v0, v0, v119, v106
	v_max3_f32 v14, v14, v108, v109
	v_max3_f32 v0, v0, v107, v122
	v_max3_f32 v14, v14, v124, v125
	v_max3_f32 v0, v0, v123, v110
	v_max3_f32 v14, v14, v112, v113
	v_max3_f32 v0, v0, v111, v126
	v_max3_f32 v14, v14, v128, v129
	v_mfma_f32_32x32x16_bf16 v[16:31], v[162:165], v[220:223], v[16:31]
	v_max3_f32 v0, v0, v127, v14
	v_mov_b32_e32 v14, v0
	s_nop 1
	v_permlane32_swap_b32_e32 v0, v14
	v_max_f32_e32 v14, v14, v14
	v_max_f32_e32 v0, v0, v0
	v_max_f32_e32 v167, v0, v14
	s_barrier
	s_branch .Lafter_max_1
.LBB0_381:
	s_add_i32 s46, s47, -1
	s_add_i32 s72, s72, 1
	s_add_i32 s14, s39, -1
	s_cmp_lt_i32 s46, s23
	s_cselect_b32 s14, s72, s14
	s_lshl_b32 s14, s14, 6
	v_cvt_f32_i32_e32 v0, s14
	s_barrier
	v_sub_f32_e32 v0, v192, v0
	v_sub_f32_e32 v14, 0, v0
	v_sub_f32_e32 v15, 0x42000000, v0
	s_nop 0
	v_fma_f32 v98, v81, |v14|, v98
	v_sub_f32_e32 v14, 0x3f800000, v0
	v_fma_f32 v114, v81, |v15|, v114
	v_sub_f32_e32 v15, 0x42040000, v0
	s_nop 0
	v_fma_f32 v99, v81, |v14|, v99
	v_sub_f32_e32 v14, 0x40000000, v0
	v_fma_f32 v115, v81, |v15|, v115
	v_sub_f32_e32 v15, 0x42080000, v0
	s_nop 0
	v_fma_f32 v100, v81, |v14|, v100
	v_sub_f32_e32 v14, 0x40400000, v0
	v_fma_f32 v116, v81, |v15|, v116
	v_sub_f32_e32 v15, 0x420c0000, v0
	s_nop 0
	v_fma_f32 v101, v81, |v14|, v101
	v_sub_f32_e32 v14, 0x41000000, v0
	v_fma_f32 v117, v81, |v15|, v117
	v_sub_f32_e32 v15, 0x42200000, v0
	s_nop 0
	v_fma_f32 v102, v81, |v14|, v102
	v_sub_f32_e32 v14, 0x41100000, v0
	v_fma_f32 v118, v81, |v15|, v118
	v_sub_f32_e32 v15, 0x42240000, v0
	s_nop 0
	v_fma_f32 v103, v81, |v14|, v103
	v_sub_f32_e32 v14, 0x41200000, v0
	v_fma_f32 v119, v81, |v15|, v119
	v_sub_f32_e32 v15, 0x42280000, v0
	s_nop 0
	v_fma_f32 v104, v81, |v14|, v104
	v_sub_f32_e32 v14, 0x41300000, v0
	v_fma_f32 v120, v81, |v15|, v120
	v_sub_f32_e32 v15, 0x422c0000, v0
	s_nop 0
	v_fma_f32 v105, v81, |v14|, v105
	v_sub_f32_e32 v14, 0x41800000, v0
	v_fma_f32 v121, v81, |v15|, v121
	v_sub_f32_e32 v15, 0x42400000, v0
	s_nop 0
	v_fma_f32 v106, v81, |v14|, v106
	v_sub_f32_e32 v14, 0x41880000, v0
	v_fma_f32 v122, v81, |v15|, v122
	v_sub_f32_e32 v15, 0x42440000, v0
	s_nop 0
	v_fma_f32 v107, v81, |v14|, v107
	v_sub_f32_e32 v14, 0x41900000, v0
	v_fma_f32 v123, v81, |v15|, v123
	v_sub_f32_e32 v15, 0x42480000, v0
	s_nop 0
	v_fma_f32 v108, v81, |v14|, v108
	v_sub_f32_e32 v14, 0x41980000, v0
	v_fma_f32 v124, v81, |v15|, v124
	v_sub_f32_e32 v15, 0x424c0000, v0
	s_nop 0
	v_fma_f32 v109, v81, |v14|, v109
	v_sub_f32_e32 v14, 0x41c00000, v0
	v_fma_f32 v125, v81, |v15|, v125
	v_sub_f32_e32 v15, 0x42600000, v0
	s_nop 0
	v_fma_f32 v110, v81, |v14|, v110
	v_sub_f32_e32 v14, 0x41c80000, v0
	v_fma_f32 v126, v81, |v15|, v126
	v_sub_f32_e32 v15, 0x42640000, v0
	s_nop 0
	v_fma_f32 v111, v81, |v14|, v111
	v_sub_f32_e32 v14, 0x41d00000, v0
	v_fma_f32 v127, v81, |v15|, v127
	v_sub_f32_e32 v15, 0x42680000, v0
	s_nop 0
	v_fma_f32 v112, v81, |v14|, v112
	v_sub_f32_e32 v14, 0x41d80000, v0
	v_sub_f32_e32 v0, 0x426c0000, v0
	v_fma_f32 v128, v81, |v15|, v128
	s_nop 0
	v_fma_f32 v113, v81, |v14|, v113
	v_fma_f32 v129, v81, |v0|, v129
	v_max_f32_e32 v0, v99, v99
	v_max_f32_e32 v14, v98, v98
	v_max_f32_e32 v0, v14, v0
	v_max3_f32 v14, v100, v101, v115
	v_max3_f32 v0, v0, v114, v116
	v_max3_f32 v0, v0, v117, v102
	v_max3_f32 v14, v14, v104, v105
	v_max3_f32 v0, v0, v103, v118
	v_max3_f32 v14, v14, v120, v121
	v_max3_f32 v0, v0, v119, v106
	v_max3_f32 v14, v14, v108, v109
	v_max3_f32 v0, v0, v107, v122
	v_max3_f32 v14, v14, v124, v125
	v_max3_f32 v0, v0, v123, v110
	v_max3_f32 v14, v14, v112, v113
	v_max3_f32 v0, v0, v111, v126
	v_max3_f32 v14, v14, v128, v129
	v_max3_f32 v0, v0, v127, v14
	v_mov_b32_e32 v14, v0
	s_nop 1
	v_permlane32_swap_b32_e32 v0, v14
	v_max_f32_e32 v14, v14, v14
	v_max_f32_e32 v0, v0, v0
	v_max_f32_e32 v167, v0, v14
.Lafter_max_1:
	v_pk_add_f32 v[14:15], v[172:173], v[166:167]
	v_mov_b32_e32 v0, 1.0
	v_cmp_lt_f32_e32 vcc, v15, v14
	s_cmp_lg_u64 vcc, exec
	s_cselect_b64 s[14:15], -1, 0
	s_cmp_eq_u64 vcc, exec
	s_cbranch_scc1 .LBB0_385
	v_cmp_ge_f32_e32 vcc, s59, v167
	s_cmp_eq_u64 vcc, exec
	s_cbranch_scc0 .LBB0_396
	v_mov_b32_e32 v0, 1.0
